# seams: non-leader workgroups poll the cross-XCD release generation directly (one hop less per grid barrier)
# speedup vs baseline: 1.0238x; 1.0238x over previous
.LBB0_104:
	s_lshl_b32 s0, s90, 8
	v_readlane_b32 s8, v254, 10
	v_readlane_b32 s9, v254, 11
	s_add_u32 s0, s8, s0
	s_addc_u32 s1, s9, 0
	v_mov_b32_e32 v1, 0x1000
	v_mov_b32_e32 v3, 1
	global_atomic_add v3, v1, v3, s[0:1] offset:1024 sc0
	v_cvt_f32_u32_e32 v1, v2
	v_sub_u32_e32 v4, 0, v2
	v_rcp_iflag_f32_e32 v1, v1
	s_nop 0
	v_mul_f32_e32 v1, 0x4f7ffffe, v1
	v_cvt_u32_f32_e32 v1, v1
	v_mul_lo_u32 v4, v4, v1
	v_mul_hi_u32 v4, v1, v4
	v_add_u32_e32 v1, v1, v4
	s_waitcnt vmcnt(0)
	v_mul_hi_u32 v1, v3, v1
	v_mul_lo_u32 v4, v1, v2
	v_sub_u32_e32 v4, v3, v4
	v_add_u32_e32 v5, 1, v1
	v_cmp_ge_u32_e32 vcc, v4, v2
	v_add_u32_e32 v3, 1, v3
	s_nop 0
	v_cndmask_b32_e32 v1, v1, v5, vcc
	v_sub_u32_e32 v5, v4, v2
	v_cndmask_b32_e32 v4, v4, v5, vcc
	v_add_u32_e32 v5, 1, v1
	v_cmp_ge_u32_e32 vcc, v4, v2
	s_nop 1
	v_cndmask_b32_e32 v1, v1, v5, vcc
	v_mul_lo_u32 v4, v2, v1
	v_add_u32_e32 v2, v4, v2
	v_cmp_ne_u32_e32 vcc, v3, v2
	s_and_saveexec_b64 s[8:9], vcc
	s_xor_b64 s[8:9], exec, s[8:9]
	s_cbranch_execz .LBB0_118
	s_waitcnt lgkmcnt(0)
	v_mov_b32_e32 v0, 0x1e03500
	global_load_dword v0, v0, s[78:79] sc1
	s_add_u32 s14, s78, 0x1e03500
	s_addc_u32 s15, s79, 0
	s_waitcnt vmcnt(0)
	v_cmp_eq_u32_e32 vcc, v0, v1
	s_and_saveexec_b64 s[10:11], vcc
	s_cbranch_execz .LBB0_117
	s_add_u32 s12, s78, 0x1e00200
	s_addc_u32 s13, s79, 0
	s_mov_b32 s3, 1
	s_mov_b64 s[20:21], 0
	v_mov_b32_e32 v0, 0
	s_branch .LBB0_108

.LBB0_163:
	s_lshl_b32 s3, s90, 8
	v_readlane_b32 s6, v254, 10
	v_readlane_b32 s7, v254, 11
	s_add_u32 s6, s6, s3
	s_addc_u32 s7, s7, 0
	v_mov_b32_e32 v1, 0x1000
	v_mov_b32_e32 v3, 1
	v_sub_u32_e32 v4, 0, v2
	global_atomic_add v3, v1, v3, s[6:7] offset:1024 sc0
	v_cvt_f32_u32_e32 v1, v2
	v_rcp_iflag_f32_e32 v1, v1
	s_nop 0
	v_mul_f32_e32 v1, 0x4f7ffffe, v1
	v_cvt_u32_f32_e32 v1, v1
	v_mul_lo_u32 v4, v4, v1
	v_mul_hi_u32 v4, v1, v4
	v_add_u32_e32 v1, v1, v4
	s_waitcnt vmcnt(0)
	v_mul_hi_u32 v1, v3, v1
	v_mul_lo_u32 v4, v1, v2
	v_sub_u32_e32 v4, v3, v4
	v_add_u32_e32 v5, 1, v1
	v_cmp_ge_u32_e32 vcc, v4, v2
	v_add_u32_e32 v3, 1, v3
	s_nop 0
	v_cndmask_b32_e32 v1, v1, v5, vcc
	v_sub_u32_e32 v5, v4, v2
	v_cndmask_b32_e32 v4, v4, v5, vcc
	v_add_u32_e32 v5, 1, v1
	v_cmp_ge_u32_e32 vcc, v4, v2
	s_nop 1
	v_cndmask_b32_e32 v1, v1, v5, vcc
	v_mul_lo_u32 v4, v2, v1
	v_add_u32_e32 v2, v4, v2
	v_cmp_ne_u32_e32 vcc, v3, v2
	s_and_saveexec_b64 s[8:9], vcc
	s_xor_b64 s[8:9], exec, s[8:9]
	s_cbranch_execz .LBB0_177
	s_waitcnt lgkmcnt(0)
	v_mov_b32_e32 v0, 0x1e03500
	global_load_dword v0, v0, s[78:79] sc1
	s_add_u32 s14, s78, 0x1e03500
	s_addc_u32 s15, s79, 0
	s_waitcnt vmcnt(0)
	v_cmp_eq_u32_e32 vcc, v0, v1
	s_and_saveexec_b64 s[10:11], vcc
	s_cbranch_execz .LBB0_176
	s_add_u32 s12, s78, 0x1e00200
	s_addc_u32 s13, s79, 0
	s_mov_b32 s3, 1
	s_mov_b64 s[20:21], 0
	v_mov_b32_e32 v0, 0
	s_branch .LBB0_167

.LBB0_603:
	s_lshl_b32 s3, s90, 8
	v_readlane_b32 s8, v254, 10
	v_readlane_b32 s9, v254, 11
	s_add_u32 s8, s8, s3
	s_addc_u32 s9, s9, 0
	v_mov_b32_e32 v1, 0x1000
	v_mov_b32_e32 v3, 1
	v_sub_u32_e32 v4, 0, v2
	global_atomic_add v3, v1, v3, s[8:9] offset:1024 sc0
	v_cvt_f32_u32_e32 v1, v2
	v_rcp_iflag_f32_e32 v1, v1
	s_nop 0
	v_mul_f32_e32 v1, 0x4f7ffffe, v1
	v_cvt_u32_f32_e32 v1, v1
	v_mul_lo_u32 v4, v4, v1
	v_mul_hi_u32 v4, v1, v4
	v_add_u32_e32 v1, v1, v4
	s_waitcnt vmcnt(0)
	v_mul_hi_u32 v1, v3, v1
	v_mul_lo_u32 v4, v1, v2
	v_sub_u32_e32 v4, v3, v4
	v_add_u32_e32 v5, 1, v1
	v_cmp_ge_u32_e32 vcc, v4, v2
	v_add_u32_e32 v3, 1, v3
	s_nop 0
	v_cndmask_b32_e32 v1, v1, v5, vcc
	v_sub_u32_e32 v5, v4, v2
	v_cndmask_b32_e32 v4, v4, v5, vcc
	v_add_u32_e32 v5, 1, v1
	v_cmp_ge_u32_e32 vcc, v4, v2
	s_nop 1
	v_cndmask_b32_e32 v1, v1, v5, vcc
	v_mul_lo_u32 v4, v2, v1
	v_add_u32_e32 v2, v4, v2
	v_cmp_ne_u32_e32 vcc, v3, v2
	s_and_saveexec_b64 s[10:11], vcc
	s_xor_b64 s[10:11], exec, s[10:11]
	s_cbranch_execz .LBB0_617
	s_waitcnt lgkmcnt(0)
	v_mov_b32_e32 v0, 0x1e03500
	global_load_dword v0, v0, s[78:79] sc1
	s_add_u32 s20, s78, 0x1e03500
	s_addc_u32 s21, s79, 0
	s_waitcnt vmcnt(0)
	v_cmp_eq_u32_e32 vcc, v0, v1
	s_and_saveexec_b64 s[12:13], vcc
	s_cbranch_execz .LBB0_616
	s_add_u32 s14, s78, 0x1e00200
	s_addc_u32 s15, s79, 0
	s_mov_b32 s3, 1
	s_mov_b64 s[28:29], 0
	v_mov_b32_e32 v0, 0
	s_branch .LBB0_607

.LBB0_795:
	s_lshl_b32 s3, s90, 8
	v_readlane_b32 s6, v254, 10
	v_readlane_b32 s7, v254, 11
	s_add_u32 s6, s6, s3
	s_addc_u32 s7, s7, 0
	v_mov_b32_e32 v1, 0x1000
	v_mov_b32_e32 v3, 1
	v_sub_u32_e32 v4, 0, v2
	global_atomic_add v3, v1, v3, s[6:7] offset:1024 sc0
	v_cvt_f32_u32_e32 v1, v2
	v_rcp_iflag_f32_e32 v1, v1
	s_nop 0
	v_mul_f32_e32 v1, 0x4f7ffffe, v1
	v_cvt_u32_f32_e32 v1, v1
	v_mul_lo_u32 v4, v4, v1
	v_mul_hi_u32 v4, v1, v4
	v_add_u32_e32 v1, v1, v4
	s_waitcnt vmcnt(0)
	v_mul_hi_u32 v1, v3, v1
	v_mul_lo_u32 v4, v1, v2
	v_sub_u32_e32 v4, v3, v4
	v_add_u32_e32 v5, 1, v1
	v_cmp_ge_u32_e32 vcc, v4, v2
	v_add_u32_e32 v3, 1, v3
	s_nop 0
	v_cndmask_b32_e32 v1, v1, v5, vcc
	v_sub_u32_e32 v5, v4, v2
	v_cndmask_b32_e32 v4, v4, v5, vcc
	v_add_u32_e32 v5, 1, v1
	v_cmp_ge_u32_e32 vcc, v4, v2
	s_nop 1
	v_cndmask_b32_e32 v1, v1, v5, vcc
	v_mul_lo_u32 v4, v2, v1
	v_add_u32_e32 v2, v4, v2
	v_cmp_ne_u32_e32 vcc, v3, v2
	s_and_saveexec_b64 s[8:9], vcc
	s_xor_b64 s[8:9], exec, s[8:9]
	s_cbranch_execz .LBB0_809
	s_waitcnt lgkmcnt(0)
	v_mov_b32_e32 v0, 0x1e03500
	global_load_dword v0, v0, s[78:79] sc1
	s_add_u32 s14, s78, 0x1e03500
	s_addc_u32 s15, s79, 0
	s_waitcnt vmcnt(0)
	v_cmp_eq_u32_e32 vcc, v0, v1
	s_and_saveexec_b64 s[10:11], vcc
	s_cbranch_execz .LBB0_808
	s_add_u32 s12, s78, 0x1e00200
	s_addc_u32 s13, s79, 0
	s_mov_b32 s3, 1
	s_mov_b64 s[16:17], 0
	v_mov_b32_e32 v0, 0
	s_branch .LBB0_799

.LBB0_919:
	s_lshl_b32 s3, s90, 8
	v_readlane_b32 s8, v254, 10
	v_readlane_b32 s9, v254, 11
	s_add_u32 s8, s8, s3
	s_addc_u32 s9, s9, 0
	v_mov_b32_e32 v1, 0x1000
	v_mov_b32_e32 v3, 1
	v_sub_u32_e32 v4, 0, v2
	global_atomic_add v3, v1, v3, s[8:9] offset:1024 sc0
	v_cvt_f32_u32_e32 v1, v2
	v_rcp_iflag_f32_e32 v1, v1
	s_nop 0
	v_mul_f32_e32 v1, 0x4f7ffffe, v1
	v_cvt_u32_f32_e32 v1, v1
	v_mul_lo_u32 v4, v4, v1
	v_mul_hi_u32 v4, v1, v4
	v_add_u32_e32 v1, v1, v4
	s_waitcnt vmcnt(0)
	v_mul_hi_u32 v1, v3, v1
	v_mul_lo_u32 v4, v1, v2
	v_sub_u32_e32 v4, v3, v4
	v_add_u32_e32 v5, 1, v1
	v_cmp_ge_u32_e32 vcc, v4, v2
	v_add_u32_e32 v3, 1, v3
	s_nop 0
	v_cndmask_b32_e32 v1, v1, v5, vcc
	v_sub_u32_e32 v5, v4, v2
	v_cndmask_b32_e32 v4, v4, v5, vcc
	v_add_u32_e32 v5, 1, v1
	v_cmp_ge_u32_e32 vcc, v4, v2
	s_nop 1
	v_cndmask_b32_e32 v1, v1, v5, vcc
	v_mul_lo_u32 v4, v2, v1
	v_add_u32_e32 v2, v4, v2
	v_cmp_ne_u32_e32 vcc, v3, v2
	s_and_saveexec_b64 s[10:11], vcc
	s_xor_b64 s[10:11], exec, s[10:11]
	s_cbranch_execz .LBB0_933
	s_waitcnt lgkmcnt(0)
	v_mov_b32_e32 v0, 0x1e03500
	global_load_dword v0, v0, s[78:79] sc1
	s_add_u32 s16, s78, 0x1e03500
	s_addc_u32 s17, s79, 0
	s_waitcnt vmcnt(0)
	v_cmp_eq_u32_e32 vcc, v0, v1
	s_and_saveexec_b64 s[12:13], vcc
	s_cbranch_execz .LBB0_932
	s_add_u32 s14, s78, 0x1e00200
	s_addc_u32 s15, s79, 0
	s_mov_b32 s3, 1
	s_mov_b64 s[18:19], 0
	v_mov_b32_e32 v0, 0
	s_branch .LBB0_923

.LBB0_986:
	s_lshl_b32 s4, s90, 8
	v_readlane_b32 s6, v254, 10
	v_readlane_b32 s7, v254, 11
	s_add_u32 s4, s6, s4
	s_addc_u32 s5, s7, 0
	v_mov_b32_e32 v1, 0x1000
	v_mov_b32_e32 v3, 1
	global_atomic_add v3, v1, v3, s[4:5] offset:1024 sc0
	v_cvt_f32_u32_e32 v1, v2
	v_sub_u32_e32 v4, 0, v2
	v_rcp_iflag_f32_e32 v1, v1
	s_nop 0
	v_mul_f32_e32 v1, 0x4f7ffffe, v1
	v_cvt_u32_f32_e32 v1, v1
	v_mul_lo_u32 v4, v4, v1
	v_mul_hi_u32 v4, v1, v4
	v_add_u32_e32 v1, v1, v4
	s_waitcnt vmcnt(0)
	v_mul_hi_u32 v1, v3, v1
	v_mul_lo_u32 v4, v1, v2
	v_sub_u32_e32 v4, v3, v4
	v_add_u32_e32 v5, 1, v1
	v_cmp_ge_u32_e32 vcc, v4, v2
	v_add_u32_e32 v3, 1, v3
	s_nop 0
	v_cndmask_b32_e32 v1, v1, v5, vcc
	v_sub_u32_e32 v5, v4, v2
	v_cndmask_b32_e32 v4, v4, v5, vcc
	v_add_u32_e32 v5, 1, v1
	v_cmp_ge_u32_e32 vcc, v4, v2
	s_nop 1
	v_cndmask_b32_e32 v1, v1, v5, vcc
	v_mul_lo_u32 v4, v2, v1
	v_add_u32_e32 v2, v4, v2
	v_cmp_ne_u32_e32 vcc, v3, v2
	s_and_saveexec_b64 s[6:7], vcc
	s_xor_b64 s[6:7], exec, s[6:7]
	s_cbranch_execz .LBB0_1000
	s_waitcnt lgkmcnt(0)
	v_mov_b32_e32 v0, 0x1e03500
	global_load_dword v0, v0, s[78:79] sc1
	s_add_u32 s12, s78, 0x1e03500
	s_addc_u32 s13, s79, 0
	s_waitcnt vmcnt(0)
	v_cmp_eq_u32_e32 vcc, v0, v1
	s_and_saveexec_b64 s[8:9], vcc
	s_cbranch_execz .LBB0_999
	s_add_u32 s10, s78, 0x1e00200
	s_addc_u32 s11, s79, 0
	s_mov_b32 s26, 1
	s_mov_b64 s[14:15], 0
	v_mov_b32_e32 v0, 0
	s_branch .LBB0_990
